# EpiUp: per-tile rstd table (rsL, 2 dependent load rounds + sqrt/div) recomputed only when the tile row block pm changes (same pm for 11 consecutive tiles); on top of v_peel
# baseline (speedup 1.0000x reference)
; #define SEAM(k) do { if (IN(k) && IN((k) + 1)) { if ((k) == 0) grid.sync(); else xcd_barrier(xbar); } } while (0)
; #define PH(k) if (IN(k)) for (int rep_ = 0; rep_ <= ((PROBE_DUP >> (k)) & 1); ++rep_)
;     __host__ __device__ bool next(int i, Unit& u) const {
;         const long L = (long)i * G + c; if (L >= nwg) return false;
;         int wgid = (int)L; { const int q = nwg / NXCD, r = nwg % NXCD, xcd = wgid % NXCD, off = wgid / NXCD; wgid = (xcd < r ? xcd * (q + 1) : r * (q + 1) + (xcd - r) * q) + off; }
;         const int nig = WGM * nN, gid = wgid / nig, fm = gid * WGM, gsz = (nM - fm) < WGM ? (nM - fm) : WGM;
;         u.pm = fm + ((wgid % nig) % gsz); u.pn = (wgid % nig) / gsz; return true;
; __global__ void __launch_bounds__(NTHR, 2) fwd_kernel(Params p) {
;     ...
;     PH(11) { if (rep_) xcd_barrier(xbar); pg8::Gemm g{(const bf16*)(ws + WS_XB), (const bf16*)(ws + WS_W_UP), T, 2 * DFF, DM}; pg8::StaticOrder S; S.init(T, 2 * DFF, G, bx);
;         pg8::EpiUp E{(bf16*)(ws + WS_ACT), (const float*)(ws + WS_SSQ1), p.in[I_CW], p.in[I_CB], (float*)(ws + WS_TOP), (float*)(ws + WS_BOT), lds + EPI_OFF};
;         pg8::gemm_phase<pg8::EpiUp, pg8::StaticOrder, true, true>(lds, g, S, E); } SEAM(11);
.LBB0_1689:
	s_cmp_lt_i32 s30, 12
	s_cselect_b64 s[8:9], -1, 0
	s_and_b64 s[0:1], s[8:9], s[4:5]
	s_andn2_b64 vcc, exec, s[0:1]
	s_cbranch_vccnz .LBB0_1731
	s_mov_b32 s99, -1
	s_cmpk_lt_i32 s96, 0x1600
	s_cselect_b64 s[0:1], -1, 0
	s_cmpk_gt_i32 s96, 0x15ff
	v_readfirstlane_b32 s34, v144
	s_cbranch_scc1 .LBB0_1692
	s_ashr_i32 s3, s96, 31
	s_lshr_b32 s3, s3, 29
	s_add_i32 s3, s96, s3
	s_ashr_i32 s5, s3, 3
	s_and_b32 s3, s3, -8
	s_sub_i32 s3, s96, s3
	s_cmp_lt_i32 s3, 0
	s_movk_i32 s6, 0x2c1
	s_cselect_b32 s6, s6, 0x2c0
	s_mul_i32 s3, s3, s6
	s_add_i32 s3, s3, s5
	s_mul_hi_i32 s5, s3, 0x2e8ba2e9
	s_lshr_b32 s6, s5, 31
	s_ashr_i32 s5, s5, 6
	s_add_i32 s5, s5, s6
	s_lshl_b32 s6, s5, 3
	s_mulk_i32 s5, 0x160
	s_sub_i32 s3, s3, s5
	s_sext_i32_i16 s5, s3
	s_bfe_u32 s5, s5, 0x3001c
	s_add_i32 s5, s3, s5
	s_sext_i32_i16 s7, s5
	s_and_b32 s5, s5, 0xfff8
	s_sub_i32 s3, s3, s5
	s_sext_i32_i16 s3, s3
	s_add_i32 s90, s6, s3
	s_ashr_i32 s38, s7, 3

;     __device__ __forceinline__ void operator()(f32x4 (&acc)[2][2][4][2], const Unit& u, int wr, int wc, int fr_, int fq_) const {
;     ...
;         if (tid < 256) { const f32x4* p = (const f32x4*)(ssq1 + (size_t)(u.pm * BM + tid) * 32); f32x4 s = p[0];
; #pragma unroll
;             for (int i = 1; i < 8; ++i) s += p[i];
;             rsL[tid] = 1.0f / sqrtf(((s[0] + s[1]) + (s[2] + s[3])) * (1.0f / 2048.0f) + 1e-6f); }
.LBB0_1704:
	v_mov_b32_e32 v178, v216
	v_mov_b32_e32 v128, v217
	s_mov_b64 s[8:9], exec
	v_readlane_b32 s0, v244, 2
	v_readlane_b32 s1, v244, 3
	s_and_b64 s[0:1], s[8:9], s[0:1]
	s_mov_b64 exec, s[0:1]
	s_cbranch_execz .LBB0_1706
	s_cmp_eq_u32 s90, s99
	s_cbranch_scc1 .LBB0_1706
	s_mov_b32 s99, s90
	v_lshl_or_b32 v130, s90, 8, v144
	v_ashrrev_i32_e32 v131, 31, v130
	v_readlane_b32 s0, v244, 47
	v_lshlrev_b64 v[130:131], 7, v[130:131]
	v_readlane_b32 s1, v244, 48
	s_nop 1
	v_lshl_add_u64 v[142:143], s[0:1], 0, v[130:131]
	global_load_dwordx4 v[130:133], v[142:143], off offset:48
	global_load_dwordx4 v[134:137], v[142:143], off offset:32
	global_load_dwordx4 v[138:141], v[142:143], off
	global_load_dwordx4 v[164:167], v[142:143], off offset:16
	s_mov_b32 s0, 0xf800000
	s_waitcnt vmcnt(0)
	v_pk_add_f32 v[140:141], v[140:141], v[166:167]
	v_pk_add_f32 v[138:139], v[138:139], v[164:165]
	v_pk_add_f32 v[136:137], v[140:141], v[136:137]
	v_pk_add_f32 v[134:135], v[138:139], v[134:135]
	v_pk_add_f32 v[168:169], v[136:137], v[132:133]
	v_pk_add_f32 v[170:171], v[134:135], v[130:131]
	global_load_dwordx4 v[130:133], v[142:143], off offset:112
	global_load_dwordx4 v[134:137], v[142:143], off offset:96
	global_load_dwordx4 v[138:141], v[142:143], off offset:80
	global_load_dwordx4 v[164:167], v[142:143], off offset:64
	s_waitcnt vmcnt(0)
	v_pk_add_f32 v[142:143], v[168:169], v[166:167]
	v_pk_add_f32 v[164:165], v[170:171], v[164:165]
	v_pk_add_f32 v[140:141], v[142:143], v[140:141]
	v_pk_add_f32 v[138:139], v[164:165], v[138:139]
	v_pk_add_f32 v[136:137], v[140:141], v[136:137]
	v_pk_add_f32 v[134:135], v[138:139], v[134:135]
	v_pk_add_f32 v[132:133], v[136:137], v[132:133]
	v_pk_add_f32 v[130:131], v[134:135], v[130:131]
	v_pk_mov_b32 v[134:135], v[130:131], v[132:133] op_sel:[1,0]
	v_mov_b32_e32 v131, v133
	v_pk_add_f32 v[130:131], v[134:135], v[130:131]
	v_add_f32_e32 v129, v130, v131
	v_fmamk_f32 v129, v129, 0x3a000000, v223
	v_cmp_gt_f32_e32 vcc, s0, v129
	v_mul_f32_e32 v130, 0x4f800000, v129
	s_nop 0
	v_cndmask_b32_e32 v129, v129, v130, vcc
	v_sqrt_f32_e32 v130, v129
	s_nop 0
	v_add_u32_e32 v131, -1, v130
	v_fma_f32 v132, -v131, v130, v129
	v_cmp_ge_f32_e64 s[0:1], 0, v132
	v_add_u32_e32 v132, 1, v130
	s_nop 0
	v_cndmask_b32_e64 v131, v130, v131, s[0:1]
	v_fma_f32 v130, -v132, v130, v129
	v_cmp_lt_f32_e64 s[0:1], 0, v130
	s_nop 1
	v_cndmask_b32_e64 v130, v131, v132, s[0:1]
	v_mul_f32_e32 v131, 0x37800000, v130
	v_cndmask_b32_e32 v130, v130, v131, vcc
	v_cmp_class_f32_e32 vcc, v129, v224
	s_nop 1
	v_cndmask_b32_e32 v129, v130, v129, vcc
	v_div_scale_f32 v130, s[0:1], v129, v129, 1.0
	v_rcp_f32_e32 v131, v130
	s_nop 0
	v_fma_f32 v132, -v130, v131, 1.0
	v_fmac_f32_e32 v131, v132, v131
	v_div_scale_f32 v132, vcc, 1.0, v129, 1.0
	v_mul_f32_e32 v133, v132, v131
	v_fma_f32 v134, -v130, v133, v132
	v_fmac_f32_e32 v133, v134, v131
	v_fma_f32 v130, -v130, v133, v132
	v_div_fmas_f32 v130, v130, v131, v133
	v_div_fixup_f32 v129, v130, v129, 1.0
	ds_write_b32 v218, v129
